# P2: nine E3-only parameter loads moved from the item-top load burst to the end of stage E1 (in flight during E2, waited at E3 start)
# speedup vs baseline: 1.0181x; 1.0069x over previous
; __device__ void rwkv_prep_item(const Params& p, char* lds_, int item, PrepRaw& raw, int next_item) {
;     ...
;   {
;     const int cbp = hd * 64 + cg8;
; #pragma unroll
;     for (int q = 0; q < 2; ++q) {
;       pdb[q] = *(const f32x4*)(p.decay_bias + cbp + 4 * q); pib[q] = *(const f32x4*)(p.iclr_bias + cbp + 4 * q);
;       pkk[q] = *(const f32x4*)(p.k_k + cbp + 4 * q); pka[q] = *(const f32x4*)(p.k_a + cbp + 4 * q); prk[q] = *(const f32x4*)(p.r_k + cbp + 4 * q);
;     }
;   }
;   __syncthreads();
;   {
;     auto ldshift = [&](int col, float (&o)[8], const u32x4 cur) {
;       u32x4 prv; prv.x = prv.y = prv.z = prv.w = 0u;
;       if (hasprev) prv = *(const u32x4*)(prow - PBW + col);
.LBB0_277:
	s_and_b32 s55, s54, 0x1c0
	v_or_b32_e32 v23, s55, v116
	v_lshlrev_b32_e32 v22, 2, v23
	global_load_dwordx4 v[66:69], v22, s[64:65]
	v_add_lshl_u32 v192, s55, v240, 7
	v_mov_b32_e32 v193, 0
	v_mov_b64_e32 v[158:159], v[192:193]
	v_lshl_add_u64 v[192:193], v[136:137], 0, v[192:193]
	global_load_dwordx4 v[192:195], v[192:193], off
	v_lshl_add_u64 v[158:159], v[134:135], 0, v[158:159]
	global_load_dwordx4 v[158:161], v[158:159], off
	global_load_dwordx4 v[196:199], v[132:133], off offset:16
	global_load_dwordx4 v[200:203], v[132:133], off
	s_lshl_b32 s57, s54, 6
	s_ashr_i32 s56, s54, 9
	s_and_b32 s57, s57, 0xfc0
	v_add_u32_e32 v118, s57, v240
	s_ashr_i32 s57, s56, 31
	s_lshl_b64 s[56:57], s[56:57], 12
	v_lshl_add_u64 v[24:25], s[56:57], 0, v[118:119]
	v_mov_b64_e32 v[26:27], s[78:79]
	v_mad_u64_u32 v[156:157], s[56:57], v24, s53, v[26:27]
	v_mad_i32_i24 v157, v25, s53, v157
	v_cmp_ne_u32_e32 vcc, 0, v118
	v_lshlrev_b32_e32 v118, 1, v23
	v_mov_b32_e32 v78, 0
	v_mov_b32_e32 v79, 0
	v_mov_b32_e32 v80, 0
	v_mov_b32_e32 v81, 0
	s_barrier
	s_and_saveexec_b64 s[56:57], vcc
	s_cbranch_execz .LBB0_279
	v_lshl_add_u64 v[24:25], v[156:157], 0, v[118:119]
	global_load_dwordx4 v[78:81], v[24:25], off offset:-3328

; __device__ __forceinline__ unsigned pk2(float lo, float hi) { f32x2_t v = {lo, hi}; bf16x2_t b = __builtin_convertvector(v, bf16x2_t); return __builtin_bit_cast(unsigned, b); }
; __device__ __forceinline__ float bflo(unsigned v) { return __uint_as_float(v << 16); }
; __device__ __forceinline__ float bfhi(unsigned v) { return __uint_as_float(v & 0xffff0000u); }
; __device__ __forceinline__ float fexp(float x) { return __builtin_amdgcn_exp2f(x * 1.44269504088896f); }
; __device__ void rwkv_prep_item(const Params& p, char* lds_, int item, PrepRaw& raw, int next_item) {
;     ...
;     auto ldshift = [&](int col, float (&o)[8], const u32x4 cur) {
;       u32x4 prv; prv.x = prv.y = prv.z = prv.w = 0u;
;       if (hasprev) prv = *(const u32x4*)(prow - PBW + col);
;       const f32x4 m0 = *(const f32x4*)(p.shift_mu + col), m1 = *(const f32x4*)(p.shift_mu + col + 4);
;       const unsigned cw[4] = {cur.x, cur.y, cur.z, cur.w}, pw[4] = {prv.x, prv.y, prv.z, prv.w};
; #pragma unroll
;       for (int q = 0; q < 4; ++q) {
;         const float c0 = bflo(cw[q]), c1 = bfhi(cw[q]), p0 = bflo(pw[q]), p1 = bfhi(pw[q]);
;         const float mu0 = (q < 2) ? m0[2 * q] : m1[2 * q - 4], mu1 = (q < 2) ? m0[2 * q + 1] : m1[2 * q - 3];
;         o[2 * q] = c0 + (p0 - c0) * mu0;
;         o[2 * q + 1] = c1 + (p1 - c1) * mu1;
;       }
;     };
;     ldshift(hd * 64 + cg8, rr, raw.cur[0]);
;     ldshift(512 + hd * 64 + cg8, kk_, raw.cur[1]);
;     ldshift(1024 + hd * 64 + cg8, vv, raw.cur[2]);
;     float wd[8], ad[8];
;     ldshift(1536 + cg8, wd, raw.cur[3]);
;     ldshift(1600 + cg8, ad, raw.cur[4]);
;     u32x4 w;
;     float th[8];
; #pragma unroll
;     for (int e = 0; e < 8; ++e) th[e] = 1.f - 2.f * __builtin_amdgcn_rcpf(1.f + fexp(2.f * wd[e]));
;     w.x = pk2(th[0], th[1]); w.y = pk2(th[2], th[3]); w.z = pk2(th[4], th[5]); w.w = pk2(th[6], th[7]);
.LBB0_291:
	s_or_b64 exec, exec, s[56:57]
	s_waitcnt vmcnt(19)
	v_lshlrev_b32_e32 v118, 16, v10
	v_and_b32_e32 v155, 0xffff0000, v10
	s_waitcnt vmcnt(2)
	v_lshlrev_b32_e32 v156, 16, v102
	v_and_b32_e32 v102, 0xffff0000, v102
	v_sub_f32_e32 v156, v156, v118
	v_sub_f32_e32 v102, v102, v155
	s_waitcnt vmcnt(0)
	v_fmac_f32_e32 v118, v110, v156
	v_fmac_f32_e32 v155, v111, v102
	v_lshlrev_b32_e32 v110, 16, v11
	v_lshlrev_b32_e32 v102, 16, v103
	v_and_b32_e32 v111, 0xffff0000, v11
	v_and_b32_e32 v103, 0xffff0000, v103
	v_sub_f32_e32 v102, v102, v110
	v_fmac_f32_e32 v110, v112, v102
	v_sub_f32_e32 v102, v103, v111
	v_fmac_f32_e32 v111, v113, v102
	v_lshlrev_b32_e32 v112, 16, v12
	v_lshlrev_b32_e32 v102, 16, v104
	v_and_b32_e32 v113, 0xffff0000, v12
	v_and_b32_e32 v103, 0xffff0000, v104
	v_sub_f32_e32 v102, v102, v112
	v_fmac_f32_e32 v112, v106, v102
	v_sub_f32_e32 v102, v103, v113
	v_fmac_f32_e32 v113, v107, v102
	v_and_b32_e32 v102, 0xffff0000, v105
	v_and_b32_e32 v156, 0xffff0000, v13
	v_sub_f32_e32 v102, v102, v156
	v_lshlrev_b32_e32 v103, 16, v105
	v_lshlrev_b32_e32 v157, 16, v13
	v_fmac_f32_e32 v156, v109, v102
	v_and_b32_e32 v104, 0xffff0000, v2
	v_lshlrev_b32_e32 v102, 16, v90
	v_and_b32_e32 v90, 0xffff0000, v90
	v_sub_f32_e32 v103, v103, v157
	v_lshlrev_b32_e32 v105, 16, v2
	v_sub_f32_e32 v90, v90, v104
	v_fmac_f32_e32 v157, v108, v103
	v_sub_f32_e32 v102, v102, v105
	v_fmac_f32_e32 v104, v99, v90
	v_lshlrev_b32_e32 v103, 16, v3
	v_lshlrev_b32_e32 v90, 16, v91
	v_fmac_f32_e32 v105, v98, v102
	v_and_b32_e32 v102, 0xffff0000, v3
	v_and_b32_e32 v91, 0xffff0000, v91
	v_sub_f32_e32 v90, v90, v103
	v_fmac_f32_e32 v103, v100, v90
	v_sub_f32_e32 v90, v91, v102
	v_fmac_f32_e32 v102, v101, v90
	v_lshlrev_b32_e32 v99, 16, v4
	v_lshlrev_b32_e32 v90, 16, v92
	v_and_b32_e32 v98, 0xffff0000, v4
	v_and_b32_e32 v91, 0xffff0000, v92
	v_sub_f32_e32 v90, v90, v99
	v_fmac_f32_e32 v99, v94, v90
	v_sub_f32_e32 v90, v91, v98
	v_fmac_f32_e32 v98, v95, v90
	v_and_b32_e32 v90, 0xffff0000, v93
	v_and_b32_e32 v92, 0xffff0000, v5
	v_lshlrev_b32_e32 v91, 16, v93
	v_lshlrev_b32_e32 v93, 16, v5
	v_sub_f32_e32 v90, v90, v92
	v_sub_f32_e32 v91, v91, v93
	v_fmac_f32_e32 v92, v97, v90
	v_and_b32_e32 v90, 0xffff0000, v6
	v_lshlrev_b32_e32 v94, 16, v78
	v_and_b32_e32 v78, 0xffff0000, v78
	v_fmac_f32_e32 v93, v96, v91
	v_lshlrev_b32_e32 v91, 16, v6
	v_sub_f32_e32 v78, v78, v90
	v_sub_f32_e32 v94, v94, v91
	v_fmac_f32_e32 v90, v87, v78
	v_lshlrev_b32_e32 v87, 16, v7
	v_lshlrev_b32_e32 v78, 16, v79
	v_fmac_f32_e32 v91, v86, v94
	v_and_b32_e32 v86, 0xffff0000, v7
	v_and_b32_e32 v79, 0xffff0000, v79
	v_sub_f32_e32 v78, v78, v87
	v_fmac_f32_e32 v87, v88, v78
	v_sub_f32_e32 v78, v79, v86
	v_fmac_f32_e32 v86, v89, v78
	v_lshlrev_b32_e32 v89, 16, v8
	v_lshlrev_b32_e32 v78, 16, v80
	v_and_b32_e32 v88, 0xffff0000, v8
	v_and_b32_e32 v79, 0xffff0000, v80
	v_sub_f32_e32 v78, v78, v89
	v_fmac_f32_e32 v89, v78, v82
	v_sub_f32_e32 v78, v79, v88
	v_fmac_f32_e32 v88, v78, v83
	v_and_b32_e32 v78, 0xffff0000, v81
	v_lshlrev_b32_e32 v79, 16, v81
	v_and_b32_e32 v82, 0xffff0000, v9
	v_lshlrev_b32_e32 v83, 16, v9
	v_sub_f32_e32 v79, v79, v83
	v_sub_f32_e32 v78, v78, v82
	v_fmac_f32_e32 v83, v79, v84
	v_fmac_f32_e32 v82, v78, v85
	v_add_f32_e32 v84, v118, v118
	v_add_f32_e32 v85, v155, v155
	v_add_f32_e32 v100, v110, v110
	v_add_f32_e32 v101, v111, v111
	v_add_f32_e32 v106, v112, v112
	v_add_f32_e32 v107, v113, v113
	v_add_f32_e32 v108, v157, v157
	v_add_f32_e32 v109, v156, v156
	v_mul_f32_e32 v84, 0x3fb8aa3b, v84
	v_mul_f32_e32 v85, 0x3fb8aa3b, v85
	v_mul_f32_e32 v100, 0x3fb8aa3b, v100
	v_mul_f32_e32 v101, 0x3fb8aa3b, v101
	v_mul_f32_e32 v106, 0x3fb8aa3b, v106
	v_mul_f32_e32 v107, 0x3fb8aa3b, v107
	v_mul_f32_e32 v108, 0x3fb8aa3b, v108
	v_mul_f32_e32 v109, 0x3fb8aa3b, v109
	v_exp_f32_e32 v84, v84
	v_exp_f32_e32 v85, v85
	v_exp_f32_e32 v100, v100
	v_exp_f32_e32 v101, v101
	v_exp_f32_e32 v106, v106
	v_exp_f32_e32 v107, v107
	v_exp_f32_e32 v108, v108
	v_exp_f32_e32 v109, v109
	v_lshlrev_b32_e32 v110, 16, v14
	v_and_b32_e32 v111, 0xffff0000, v14
	v_lshlrev_b32_e32 v112, 16, v74
	v_and_b32_e32 v113, 0xffff0000, v74
	v_pk_add_f32 v[112:113], v[112:113], v[110:111] neg_lo:[0,1] neg_hi:[0,1]
	v_add_f32_e32 v84, 1.0, v84
	v_add_f32_e32 v85, 1.0, v85
	v_add_f32_e32 v100, 1.0, v100
	v_add_f32_e32 v101, 1.0, v101
	v_add_f32_e32 v106, 1.0, v106
	v_add_f32_e32 v107, 1.0, v107
	v_add_f32_e32 v108, 1.0, v108
	v_add_f32_e32 v109, 1.0, v109
	v_lshlrev_b32_e32 v74, 16, v75
	v_and_b32_e32 v75, 0xffff0000, v75
	v_rcp_f32_e32 v84, v84
	v_rcp_f32_e32 v85, v85
	v_rcp_f32_e32 v100, v100
	v_rcp_f32_e32 v101, v101
	v_rcp_f32_e32 v106, v106
	v_rcp_f32_e32 v107, v107
	v_rcp_f32_e32 v108, v108
	v_rcp_f32_e32 v109, v109
	v_pk_fma_f32 v[84:85], v[84:85], 2.0, 1.0 op_sel_hi:[1,0,0] neg_lo:[1,0,0] neg_hi:[1,0,0]
	v_pk_fma_f32 v[100:101], v[100:101], 2.0, 1.0 op_sel_hi:[1,0,0] neg_lo:[1,0,0] neg_hi:[1,0,0]
	v_pk_fma_f32 v[106:107], v[106:107], 2.0, 1.0 op_sel_hi:[1,0,0] neg_lo:[1,0,0] neg_hi:[1,0,0]
	v_pk_fma_f32 v[108:109], v[108:109], 2.0, 1.0 op_sel_hi:[1,0,0] neg_lo:[1,0,0] neg_hi:[1,0,0]
	v_add_lshl_u32 v118, s55, v240, 7
	v_mul_f32_e32 v67, v67, v104
	v_mul_f32_e32 v66, v66, v105
	v_mul_f32_e32 v68, v68, v103
	v_mul_f32_e32 v69, v69, v102
	s_add_i32 s90, s54, s50
	s_waitcnt vmcnt(0)
; __device__ __forceinline__ unsigned pk2(float lo, float hi) { f32x2_t v = {lo, hi}; bf16x2_t b = __builtin_convertvector(v, bf16x2_t); return __builtin_bit_cast(unsigned, b); }
; __device__ void rwkv_prep_item(const Params& p, char* lds_, int item, PrepRaw& raw, int next_item) {
;     ...
;     const int cbp = hd * 64 + cg8;
; #pragma unroll
;     for (int q = 0; q < 2; ++q) {
;       pdb[q] = *(const f32x4*)(p.decay_bias + cbp + 4 * q); pib[q] = *(const f32x4*)(p.iclr_bias + cbp + 4 * q);
;       pkk[q] = *(const f32x4*)(p.k_k + cbp + 4 * q); pka[q] = *(const f32x4*)(p.k_a + cbp + 4 * q); prk[q] = *(const f32x4*)(p.r_k + cbp + 4 * q);
;     }
;     ...
;     w.x = pk2(th[0], th[1]); w.y = pk2(th[2], th[3]); w.z = pk2(th[4], th[5]); w.w = pk2(th[6], th[7]);
;     *(u32x4*)(TW + t * LD + cg8) = w;
;     w.x = pk2(ad[0], ad[1]); w.y = pk2(ad[2], ad[3]); w.z = pk2(ad[4], ad[5]); w.w = pk2(ad[6], ad[7]);
;     *(u32x4*)(AD + t * LD + cg8) = w;
;     *(u32x4*)(DUs + t * LD + cg8) = *(const u32x4*)(p.DUt + (size_t)(hd * 64 + t) * 64 + cg8);
;     *(u32x4*)(IUs + t * LD + cg8) = *(const u32x4*)(p.IUt + (size_t)(hd * 64 + t) * 64 + cg8);
;   }
;   __syncthreads();
;   const int it = wave >> 1, jt0 = (wave & 1) * 2, mr = lane & 15, mg = lane >> 4;
;   const int mi = it * 16 + mr;
;   {
;     f32x4 a1[2], a2[2]; zero2(a1); zero2(a2);
;     mm_nt(TW, DUs, a1, wave, lane);
;     mm_nt(AD, IUs, a2, wave, lane);
; #pragma unroll
;     for (int jj = 0; jj < 2; ++jj) {
;       *(f32x4*)(Zw + mi * 68 + (jt0 + jj) * 16 + 4 * mg) = a1[jj];
;       *(f32x4*)(Za + mi * 68 + (jt0 + jj) * 16 + 4 * mg) = a2[jj];
;     }
;   }
;   __syncthreads();
	v_pk_fma_f32 v[94:95], v[200:201], v[112:113], v[110:111]
	v_lshlrev_b32_e32 v110, 16, v15
	v_and_b32_e32 v111, 0xffff0000, v15
	v_pk_add_f32 v[74:75], v[74:75], v[110:111] neg_lo:[0,1] neg_hi:[0,1]
	s_nop 0
	v_pk_fma_f32 v[96:97], v[202:203], v[74:75], v[110:111]
	v_lshlrev_b32_e32 v74, 16, v16
	v_and_b32_e32 v75, 0xffff0000, v16
	v_lshlrev_b32_e32 v110, 16, v76
	v_and_b32_e32 v111, 0xffff0000, v76
	v_pk_add_f32 v[110:111], v[110:111], v[74:75] neg_lo:[0,1] neg_hi:[0,1]
	v_lshlrev_b32_e32 v76, 16, v17
	v_pk_fma_f32 v[78:79], v[196:197], v[110:111], v[74:75]
	v_lshlrev_b32_e32 v74, 16, v77
	v_and_b32_e32 v75, 0xffff0000, v77
	v_and_b32_e32 v77, 0xffff0000, v17
	v_pk_add_f32 v[74:75], v[74:75], v[76:77] neg_lo:[0,1] neg_hi:[0,1]
	s_nop 0
	v_pk_fma_f32 v[80:81], v[198:199], v[74:75], v[76:77]
	v_cvt_pk_bf16_f32 v74, v84, v85
	v_cvt_pk_bf16_f32 v75, v100, v101
	v_cvt_pk_bf16_f32 v76, v106, v107
	v_cvt_pk_bf16_f32 v77, v108, v109
	ds_write_b128 v117, v[74:77]
	v_cvt_pk_bf16_f32 v74, v94, v95
	v_cvt_pk_bf16_f32 v75, v96, v97
	v_cvt_pk_bf16_f32 v76, v78, v79
	v_cvt_pk_bf16_f32 v77, v80, v81
	ds_write_b128 v117, v[74:77] offset:9216
	v_mul_f32_e32 v85, v67, v67
	v_fmac_f32_e32 v85, v66, v66
	v_fmac_f32_e32 v85, v68, v68
	v_fmac_f32_e32 v85, v69, v69
	ds_write_b128 v117, v[158:161] offset:18432
	ds_write_b128 v117, v[192:195] offset:27648
	v_or_b32_e32 v58, s55, v116
	v_lshlrev_b32_e32 v58, 2, v58
	global_load_dwordx4 v[34:37], v58, s[62:63] offset:16
	global_load_dwordx4 v[38:41], v58, s[62:63]
	global_load_dwordx4 v[54:57], v58, s[80:81] offset:16
	global_load_dwordx4 v[70:73], v58, s[80:81]
	global_load_dwordx4 v[46:49], v58, s[64:65] offset:16
	global_load_dwordx4 v[50:53], v58, s[66:67] offset:16
	global_load_dwordx4 v[62:65], v58, s[66:67]
	global_load_dwordx4 v[42:45], v58, s[82:83] offset:16
	global_load_dwordx4 v[58:61], v58, s[82:83]
	s_waitcnt lgkmcnt(0)
	s_barrier
	ds_read_b128 v[74:77], v162
	ds_read_b128 v[78:81], v163
	ds_read_b128 v[94:97], v163 offset:2304
	s_waitcnt lgkmcnt(1)
	v_mfma_f32_16x16x32_bf16 v[78:81], v[78:81], v[74:77], 0
	s_waitcnt lgkmcnt(0)
	v_mfma_f32_16x16x32_bf16 v[74:77], v[94:97], v[74:77], 0
	ds_read_b128 v[94:97], v162 offset:64
	ds_read_b128 v[106:109], v164
	s_waitcnt lgkmcnt(0)
	v_mfma_f32_16x16x32_bf16 v[78:81], v[106:109], v[94:97], v[78:81]
	ds_read_b128 v[106:109], v165 offset:2304
	s_waitcnt lgkmcnt(0)
	v_mfma_f32_16x16x32_bf16 v[74:77], v[106:109], v[94:97], v[74:77]
	ds_read_b128 v[94:97], v166
	ds_read_b128 v[106:109], v167
	ds_read_b128 v[110:113], v167 offset:2304
	s_waitcnt lgkmcnt(1)
	v_mfma_f32_16x16x32_bf16 v[106:109], v[106:109], v[94:97], 0
	s_waitcnt lgkmcnt(0)
	v_mfma_f32_16x16x32_bf16 v[94:97], v[110:113], v[94:97], 0
	ds_read_b128 v[110:113], v166 offset:64
	ds_read_b128 v[192:195], v168
	s_waitcnt lgkmcnt(0)
	v_mfma_f32_16x16x32_bf16 v[106:109], v[192:195], v[110:113], v[106:109]
	ds_read_b128 v[192:195], v169 offset:2304
	s_waitcnt lgkmcnt(0)
	v_mfma_f32_16x16x32_bf16 v[94:97], v[192:195], v[110:113], v[94:97]
	ds_write_b128 v170, v[78:81]
	s_nop 3
	ds_write_b128 v171, v[106:109]
	ds_write_b128 v170, v[74:77] offset:64
	s_nop 0
	ds_write_b128 v171, v[94:97] offset:64
	s_waitcnt lgkmcnt(0)
	s_barrier
; __device__ __forceinline__ float fsigmoid(float x) { return __builtin_amdgcn_rcpf(1.f + fexp(-x)); }
; __device__ void rwkv_prep_item(const Params& p, char* lds_, int item, PrepRaw& raw, int next_item) {
;     ...
;   float av[8], bv[8], k2[8], lw[8];
;   float bon;
;   {
;     float ss = 0.f; bon = 0.f;
;     float kk[8], ai[8];
; #pragma unroll
;     for (int e = 0; e < 8; ++e) {
;       const float zw = Zw[t * 68 + cg8 + e] + pdb[e >> 2][e & 3];
;       const float za = Za[t * 68 + cg8 + e] + pib[e >> 2][e & 3];
;       lw[e] = -0.6065306597126334f * fsigmoid(zw);
;       ai[e] = fsigmoid(za);
;       kk[e] = kk_[e] * pkk[e >> 2][e & 3];
;       k2[e] = kk_[e] * (1.f + (ai[e] - 1.f) * pka[e >> 2][e & 3]);
;       ss += kk[e] * kk[e];
;       bon += rr[e] * k2[e] * prk[e >> 2][e & 3];
;     }
;     ss += __shfl_xor(ss, 1); ss += __shfl_xor(ss, 2); ss += __shfl_xor(ss, 4);
;     bon += __shfl_xor(bon, 1); bon += __shfl_xor(bon, 2); bon += __shfl_xor(bon, 4);
;     const float inv = __builtin_amdgcn_rsqf(fmaxf(ss, 1e-24f));
; #pragma unroll
;     for (int e = 0; e < 8; ++e) { const float kn = kk[e] * inv; av[e] = -kn; bv[e] = kn * ai[e]; }
;   }
;   __builtin_amdgcn_sched_barrier(0);
;   if (next_item < 4096) prep_load(p, next_item, raw);
	ds_read_b128 v[74:77], v172
	ds_read_b128 v[78:81], v173
	s_waitcnt vmcnt(0) lgkmcnt(0)
	v_add_f32_e32 v70, v70, v78
	v_mul_f32_e32 v70, 0xbfb8aa3b, v70
	v_exp_f32_e32 v70, v70
	s_nop 0
	v_add_f32_e32 v70, 1.0, v70
	v_rcp_f32_e32 v70, v70
	s_nop 0
	v_add_f32_e32 v78, -1.0, v70
	v_fma_f32 v62, v62, v78, 1.0
	v_mul_f32_e32 v62, v105, v62
	v_mul_f32_e32 v78, v91, v62
	v_fma_f32 v84, v58, v78, 0
	v_add_f32_e32 v58, v71, v79
	v_mul_f32_e32 v58, 0xbfb8aa3b, v58
	v_exp_f32_e32 v58, v58
	s_nop 0
	v_add_f32_e32 v58, 1.0, v58
	v_rcp_f32_e32 v71, v58
	s_nop 0
	v_add_f32_e32 v58, -1.0, v71
	v_fma_f32 v58, v63, v58, 1.0
	v_mul_f32_e32 v63, v104, v58
	v_mul_f32_e32 v58, v90, v63
	v_fmac_f32_e32 v84, v59, v58
	v_add_f32_e32 v58, v72, v80
	v_mul_f32_e32 v58, 0xbfb8aa3b, v58
	v_exp_f32_e32 v58, v58
	s_nop 0
	v_add_f32_e32 v58, 1.0, v58
	v_rcp_f32_e32 v72, v58
	s_nop 0
	v_add_f32_e32 v58, -1.0, v72
	v_fma_f32 v58, v64, v58, 1.0
	v_mul_f32_e32 v64, v103, v58
	v_mul_f32_e32 v58, v87, v64
	v_fmac_f32_e32 v84, v60, v58
	v_add_f32_e32 v58, v73, v81
	v_mul_f32_e32 v58, 0xbfb8aa3b, v58
	v_exp_f32_e32 v58, v58
	s_nop 0
	v_add_f32_e32 v58, 1.0, v58
	v_rcp_f32_e32 v73, v58
	s_nop 0
	v_add_f32_e32 v58, -1.0, v73
	v_fma_f32 v58, v65, v58, 1.0
	v_mul_f32_e32 v65, v102, v58
	v_mul_f32_e32 v58, v86, v65
	v_fmac_f32_e32 v84, v61, v58
	ds_read_b128 v[58:61], v176
	ds_read_b128 v[78:81], v177
	s_waitcnt lgkmcnt(0)
	v_add_f32_e32 v54, v54, v78
	v_mul_f32_e32 v54, 0xbfb8aa3b, v54
	v_exp_f32_e32 v54, v54
	v_mul_f32_e32 v78, v46, v99
	v_fmac_f32_e32 v85, v78, v78
	v_add_f32_e32 v54, 1.0, v54
	v_rcp_f32_e32 v54, v54
	s_nop 0
	v_add_f32_e32 v46, -1.0, v54
	v_fma_f32 v46, v50, v46, 1.0
	v_mul_f32_e32 v46, v99, v46
	v_mul_f32_e32 v50, v89, v46
	v_fmac_f32_e32 v84, v42, v50
	v_add_f32_e32 v42, v55, v79
	v_mul_f32_e32 v42, 0xbfb8aa3b, v42
	v_exp_f32_e32 v42, v42
	v_mul_f32_e32 v55, v47, v98
	v_fmac_f32_e32 v85, v55, v55
	v_mul_f32_e32 v79, v49, v92
	v_add_f32_e32 v42, 1.0, v42
	v_rcp_f32_e32 v50, v42
	s_nop 0
	v_add_f32_e32 v42, -1.0, v50
	v_fma_f32 v42, v51, v42, 1.0
	v_mul_f32_e32 v47, v98, v42
	v_mul_f32_e32 v42, v88, v47
	v_fmac_f32_e32 v84, v43, v42
	v_add_f32_e32 v42, v56, v80
	v_mul_f32_e32 v42, 0xbfb8aa3b, v42
	v_exp_f32_e32 v42, v42
	v_mul_f32_e32 v56, v48, v93
	v_fmac_f32_e32 v85, v56, v56
	v_fmac_f32_e32 v85, v79, v79
	v_add_f32_e32 v42, 1.0, v42
	v_rcp_f32_e32 v51, v42
	s_nop 0
	v_add_f32_e32 v42, -1.0, v51
	v_fma_f32 v42, v52, v42, 1.0
	v_mul_f32_e32 v52, v93, v42
	v_mul_f32_e32 v42, v83, v52
	v_fmac_f32_e32 v84, v44, v42
	v_add_f32_e32 v42, v57, v81
	v_mul_f32_e32 v42, 0xbfb8aa3b, v42
	v_exp_f32_e32 v42, v42
	s_nop 0
	v_add_f32_e32 v42, 1.0, v42
	v_rcp_f32_e32 v57, v42
	s_nop 0
	v_add_f32_e32 v42, -1.0, v57
	v_fma_f32 v42, v53, v42, 1.0
	v_mul_f32_e32 v53, v92, v42
	v_mul_f32_e32 v42, v82, v53
	v_fmac_f32_e32 v84, v45, v42
	ds_bpermute_b32 v42, v178, v85
	s_waitcnt lgkmcnt(0)
	v_add_f32_e32 v42, v85, v42
	ds_bpermute_b32 v43, v179, v42
	s_waitcnt lgkmcnt(0)
	v_add_f32_e32 v80, v42, v43
	ds_bpermute_b32 v42, v178, v84
	ds_bpermute_b32 v81, v180, v80
	s_waitcnt lgkmcnt(1)
	v_add_f32_e32 v42, v84, v42
	ds_bpermute_b32 v43, v179, v42
	s_waitcnt lgkmcnt(0)
	v_add_f32_e32 v48, v42, v43
	ds_bpermute_b32 v49, v180, v48
	s_cmpk_gt_i32 s90, 0xfff
	s_cselect_b64 s[56:57], -1, 0
	v_mov_b64_e32 v[44:45], v[20:21]
	s_and_b64 vcc, exec, s[56:57]
	v_mov_b64_e32 v[42:43], v[18:19]
	s_cbranch_vccnz .LBB0_293
	s_ashr_i32 s58, s90, 9
	s_lshl_b32 s74, s90, 6
	s_ashr_i32 s59, s58, 31
	s_and_b32 s74, s74, 0xfc0
	s_lshl_b64 s[58:59], s[58:59], 12
	v_add_u32_e32 v118, s74, v240
	v_lshl_add_u64 v[2:3], s[58:59], 0, v[118:119]
	v_mov_b64_e32 v[4:5], s[78:79]
	s_and_b32 s55, s90, 0x1c0
	v_mad_u64_u32 v[10:11], s[58:59], v2, s53, v[4:5]
	v_mad_i32_i24 v11, v3, s53, v11
	s_lshl_b32 s74, s55, 1
	v_lshl_add_u64 v[2:3], v[10:11], 0, s[74:75]
	v_mov_b32_e32 v155, v119
	v_lshl_add_u64 v[12:13], v[2:3], 0, v[154:155]
	v_lshl_add_u64 v[14:15], v[10:11], 0, v[154:155]
	global_load_dwordx4 v[6:9], v[12:13], off
	global_load_dwordx4 v[2:5], v[12:13], off offset:1024
	global_load_dwordx4 v[42:45], v[12:13], off offset:2048
	s_nop 0
	global_load_dwordx4 v[10:13], v[14:15], off offset:3072
	s_nop 0
	global_load_dwordx4 v[14:17], v[14:15], off offset:3200
